# P1 rope epilogue: counted waits (vmcnt(14) before each row pair's first use of its rope values) instead of one vmcnt(0) after the 16 table loads; on top of v136
# speedup vs baseline: 1.0006x; 1.0006x over previous
.LBB0_352:
	v_lshlrev_b32_e32 v134, 7, v214
	v_and_or_b32 v128, v134, s79, v224
	v_lshlrev_b32_e32 v200, 2, v128
	global_load_dwordx4 v[184:187], v200, s[8:9] offset:16
	global_load_dwordx4 v[188:191], v200, s[8:9]
	v_lshl_add_u64 v[128:129], s[8:9], 0, v[200:201]
	v_add_co_u32_e32 v132, vcc, s60, v128
	v_lshl_add_u64 v[130:131], v[128:129], 0, s[30:31]
	s_nop 0
	v_addc_co_u32_e32 v133, vcc, 0, v129, vcc
	global_load_dwordx4 v[180:183], v[132:133], off
	global_load_dwordx4 v[176:179], v[130:131], off offset:16
	v_add_co_u32_e32 v132, vcc, s62, v128
	v_lshl_add_u64 v[130:131], v[128:129], 0, s[34:35]
	s_nop 0
	v_addc_co_u32_e32 v133, vcc, 0, v129, vcc
	global_load_dwordx4 v[172:175], v[132:133], off
	global_load_dwordx4 v[168:171], v[130:131], off offset:16
	v_lshl_add_u64 v[130:131], v[128:129], 0, s[36:37]
	v_add_co_u32_e32 v128, vcc, s63, v128
	v_readlane_b32 s26, v254, 45
	s_nop 0
	v_addc_co_u32_e32 v129, vcc, 0, v129, vcc
	global_load_dwordx4 v[164:167], v[128:129], off
	global_load_dwordx4 v[160:163], v[130:131], off offset:16
	v_add_u32_e32 v128, 0x4000, v134
	v_and_or_b32 v128, v128, s79, v224
	v_lshlrev_b32_e32 v200, 2, v128
	global_load_dwordx4 v[152:155], v200, s[8:9] offset:16
	global_load_dwordx4 v[156:159], v200, s[8:9]
	v_lshl_add_u64 v[128:129], s[8:9], 0, v[200:201]
	v_add_co_u32_e32 v132, vcc, s60, v128
	s_cmp_lt_u32 s92, 2
	v_readlane_b32 s27, v254, 46
	v_readlane_b32 s39, v254, 40
	v_addc_co_u32_e32 v133, vcc, 0, v129, vcc
	s_cselect_b32 s27, s27, s39
	v_readlane_b32 s39, v254, 39
	v_lshl_add_u64 v[130:131], v[128:129], 0, s[30:31]
	global_load_dwordx4 v[148:151], v[132:133], off
	global_load_dwordx4 v[144:147], v[130:131], off offset:16
	v_add_co_u32_e32 v132, vcc, s62, v128
	s_cselect_b32 s26, s26, s39
	v_lshl_add_u64 v[130:131], v[128:129], 0, s[34:35]
	v_addc_co_u32_e32 v133, vcc, 0, v129, vcc
	v_lshlrev_b32_e32 v200, 1, v216
	v_ashrrev_i32_e32 v215, 31, v214
	global_load_dwordx4 v[140:143], v[132:133], off
	global_load_dwordx4 v[136:139], v[130:131], off offset:16
	v_lshl_add_u64 v[130:131], v[128:129], 0, s[36:37]
	v_add_co_u32_e32 v128, vcc, s63, v128
	v_lshl_add_u64 v[218:219], s[26:27], 0, v[200:201]
	v_lshlrev_b64 v[216:217], 10, v[214:215]
	v_addc_co_u32_e32 v129, vcc, 0, v129, vcc
	v_lshl_add_u64 v[216:217], v[218:219], 0, v[216:217]
	global_load_dwordx4 v[132:135], v[128:129], off
	s_nop 0
	global_load_dwordx4 v[128:131], v[130:131], off offset:16
	s_waitcnt vmcnt(14)
	v_pk_mul_f32 v[228:229], v[124:125], v[188:189] op_sel:[1,1] op_sel_hi:[1,0]
	s_nop 0
	v_pk_fma_f32 v[230:231], v[124:125], v[188:189], v[228:229] neg_lo:[0,0,1] neg_hi:[0,0,1]
	v_pk_fma_f32 v[124:125], v[124:125], v[188:189], v[228:229] op_sel_hi:[0,1,1]
	v_mov_b32_e32 v124, v127
	v_pk_mul_f32 v[228:229], v[124:125], v[190:191] op_sel:[0,1] op_sel_hi:[0,0]
	v_pk_fma_f32 v[232:233], v[126:127], v[190:191], v[228:229] neg_lo:[0,0,1] neg_hi:[0,0,1]
	v_pk_fma_f32 v[126:127], v[126:127], v[190:191], v[228:229] op_sel_hi:[0,1,1]
	v_pk_mul_f32 v[228:229], v[120:121], v[184:185] op_sel:[1,1] op_sel_hi:[1,0]
	s_nop 0
	v_pk_fma_f32 v[234:235], v[120:121], v[184:185], v[228:229] neg_lo:[0,0,1] neg_hi:[0,0,1]
	v_pk_fma_f32 v[228:229], v[120:121], v[184:185], v[228:229] op_sel_hi:[0,1,1]
	v_mov_b32_e32 v120, v123
	v_pk_mul_f32 v[120:121], v[120:121], v[186:187] op_sel:[0,1] op_sel_hi:[0,0]
	v_pk_fma_f32 v[236:237], v[122:123], v[186:187], v[120:121] neg_lo:[0,0,1] neg_hi:[0,0,1]
	v_pk_fma_f32 v[122:123], v[122:123], v[186:187], v[120:121] op_sel_hi:[0,1,1]
	v_cvt_pk_bf16_f32 v120, v230, v125
	v_cvt_pk_bf16_f32 v121, v232, v127
	v_cvt_pk_bf16_f32 v122, v234, v229
	v_cvt_pk_bf16_f32 v123, v236, v123
	global_store_dwordx4 v[216:217], v[120:123], off
	s_nop 1
	v_pk_mul_f32 v[120:121], v[116:117], v[188:189] op_sel:[1,1] op_sel_hi:[1,0]
	s_nop 0
	v_pk_fma_f32 v[122:123], v[116:117], v[188:189], v[120:121] neg_lo:[0,0,1] neg_hi:[0,0,1]
	v_pk_fma_f32 v[116:117], v[116:117], v[188:189], v[120:121] op_sel_hi:[0,1,1]
	v_mov_b32_e32 v116, v119
	v_pk_mul_f32 v[120:121], v[116:117], v[190:191] op_sel:[0,1] op_sel_hi:[0,0]
	v_pk_fma_f32 v[124:125], v[118:119], v[190:191], v[120:121] neg_lo:[0,0,1] neg_hi:[0,0,1]
	v_pk_fma_f32 v[118:119], v[118:119], v[190:191], v[120:121] op_sel_hi:[0,1,1]
	v_pk_mul_f32 v[120:121], v[112:113], v[184:185] op_sel:[1,1] op_sel_hi:[1,0]
	s_nop 0
	v_pk_fma_f32 v[126:127], v[112:113], v[184:185], v[120:121] neg_lo:[0,0,1] neg_hi:[0,0,1]
	v_pk_fma_f32 v[120:121], v[112:113], v[184:185], v[120:121] op_sel_hi:[0,1,1]
	v_mov_b32_e32 v112, v115
	v_pk_mul_f32 v[112:113], v[112:113], v[186:187] op_sel:[0,1] op_sel_hi:[0,0]
	v_pk_fma_f32 v[184:185], v[114:115], v[186:187], v[112:113] neg_lo:[0,0,1] neg_hi:[0,0,1]
	v_pk_fma_f32 v[114:115], v[114:115], v[186:187], v[112:113] op_sel_hi:[0,1,1]
	v_cvt_pk_bf16_f32 v112, v122, v117
	v_cvt_pk_bf16_f32 v113, v124, v119
	v_cvt_pk_bf16_f32 v114, v126, v121
	v_cvt_pk_bf16_f32 v115, v184, v115
	global_store_dwordx4 v[216:217], v[112:115], off offset:256
	s_nop 1
	s_waitcnt vmcnt(14)
	v_pk_mul_f32 v[114:115], v[108:109], v[180:181] op_sel:[1,1] op_sel_hi:[1,0]
	v_or_b32_e32 v112, 16, v214
	v_pk_fma_f32 v[116:117], v[108:109], v[180:181], v[114:115] neg_lo:[0,0,1] neg_hi:[0,0,1]
	v_pk_fma_f32 v[108:109], v[108:109], v[180:181], v[114:115] op_sel_hi:[0,1,1]
	v_mov_b32_e32 v108, v111
	v_pk_mul_f32 v[114:115], v[108:109], v[182:183] op_sel:[0,1] op_sel_hi:[0,0]
	v_pk_fma_f32 v[118:119], v[110:111], v[182:183], v[114:115] neg_lo:[0,0,1] neg_hi:[0,0,1]
	v_pk_fma_f32 v[110:111], v[110:111], v[182:183], v[114:115] op_sel_hi:[0,1,1]
	v_pk_mul_f32 v[114:115], v[104:105], v[176:177] op_sel:[1,1] op_sel_hi:[1,0]
	v_ashrrev_i32_e32 v113, 31, v112
	v_pk_fma_f32 v[120:121], v[104:105], v[176:177], v[114:115] neg_lo:[0,0,1] neg_hi:[0,0,1]
	v_pk_fma_f32 v[114:115], v[104:105], v[176:177], v[114:115] op_sel_hi:[0,1,1]
	v_mov_b32_e32 v104, v107
	v_pk_mul_f32 v[104:105], v[104:105], v[178:179] op_sel:[0,1] op_sel_hi:[0,0]
	v_lshlrev_b64 v[112:113], 10, v[112:113]
	v_pk_fma_f32 v[122:123], v[106:107], v[178:179], v[104:105] neg_lo:[0,0,1] neg_hi:[0,0,1]
	v_pk_fma_f32 v[106:107], v[106:107], v[178:179], v[104:105] op_sel_hi:[0,1,1]
	v_lshl_add_u64 v[112:113], v[218:219], 0, v[112:113]
	v_cvt_pk_bf16_f32 v104, v116, v109
	v_cvt_pk_bf16_f32 v105, v118, v111
	v_cvt_pk_bf16_f32 v106, v120, v115
	v_cvt_pk_bf16_f32 v107, v122, v107
	global_store_dwordx4 v[112:113], v[104:107], off
	s_nop 1
	v_pk_mul_f32 v[104:105], v[100:101], v[180:181] op_sel:[1,1] op_sel_hi:[1,0]
	s_nop 0
	v_pk_fma_f32 v[106:107], v[100:101], v[180:181], v[104:105] neg_lo:[0,0,1] neg_hi:[0,0,1]
	v_pk_fma_f32 v[100:101], v[100:101], v[180:181], v[104:105] op_sel_hi:[0,1,1]
	v_mov_b32_e32 v100, v103
	v_pk_mul_f32 v[104:105], v[100:101], v[182:183] op_sel:[0,1] op_sel_hi:[0,0]
	v_pk_fma_f32 v[108:109], v[102:103], v[182:183], v[104:105] neg_lo:[0,0,1] neg_hi:[0,0,1]
	v_pk_fma_f32 v[102:103], v[102:103], v[182:183], v[104:105] op_sel_hi:[0,1,1]
	v_pk_mul_f32 v[104:105], v[96:97], v[176:177] op_sel:[1,1] op_sel_hi:[1,0]
	s_nop 0
	v_pk_fma_f32 v[110:111], v[96:97], v[176:177], v[104:105] neg_lo:[0,0,1] neg_hi:[0,0,1]
	v_pk_fma_f32 v[104:105], v[96:97], v[176:177], v[104:105] op_sel_hi:[0,1,1]
	v_mov_b32_e32 v96, v99
	v_pk_mul_f32 v[96:97], v[96:97], v[178:179] op_sel:[0,1] op_sel_hi:[0,0]
	v_pk_fma_f32 v[114:115], v[98:99], v[178:179], v[96:97] neg_lo:[0,0,1] neg_hi:[0,0,1]
	v_pk_fma_f32 v[98:99], v[98:99], v[178:179], v[96:97] op_sel_hi:[0,1,1]
	v_cvt_pk_bf16_f32 v96, v106, v101
	v_cvt_pk_bf16_f32 v97, v108, v103
	v_cvt_pk_bf16_f32 v98, v110, v105
	v_cvt_pk_bf16_f32 v99, v114, v99
	global_store_dwordx4 v[112:113], v[96:99], off offset:256
	s_nop 1
	s_waitcnt vmcnt(14)
	v_pk_mul_f32 v[98:99], v[92:93], v[172:173] op_sel:[1,1] op_sel_hi:[1,0]
	v_or_b32_e32 v96, 32, v214
	v_pk_fma_f32 v[100:101], v[92:93], v[172:173], v[98:99] neg_lo:[0,0,1] neg_hi:[0,0,1]
	v_pk_fma_f32 v[92:93], v[92:93], v[172:173], v[98:99] op_sel_hi:[0,1,1]
	v_mov_b32_e32 v92, v95
	v_pk_mul_f32 v[98:99], v[92:93], v[174:175] op_sel:[0,1] op_sel_hi:[0,0]
	v_pk_fma_f32 v[102:103], v[94:95], v[174:175], v[98:99] neg_lo:[0,0,1] neg_hi:[0,0,1]
	v_pk_fma_f32 v[94:95], v[94:95], v[174:175], v[98:99] op_sel_hi:[0,1,1]
	v_pk_mul_f32 v[98:99], v[88:89], v[168:169] op_sel:[1,1] op_sel_hi:[1,0]
	v_ashrrev_i32_e32 v97, 31, v96
	v_pk_fma_f32 v[104:105], v[88:89], v[168:169], v[98:99] neg_lo:[0,0,1] neg_hi:[0,0,1]
	v_pk_fma_f32 v[98:99], v[88:89], v[168:169], v[98:99] op_sel_hi:[0,1,1]
	v_mov_b32_e32 v88, v91
	v_pk_mul_f32 v[88:89], v[88:89], v[170:171] op_sel:[0,1] op_sel_hi:[0,0]
	v_lshlrev_b64 v[96:97], 10, v[96:97]
	v_pk_fma_f32 v[106:107], v[90:91], v[170:171], v[88:89] neg_lo:[0,0,1] neg_hi:[0,0,1]
	v_pk_fma_f32 v[90:91], v[90:91], v[170:171], v[88:89] op_sel_hi:[0,1,1]
	v_lshl_add_u64 v[96:97], v[218:219], 0, v[96:97]
	v_cvt_pk_bf16_f32 v88, v100, v93
	v_cvt_pk_bf16_f32 v89, v102, v95
	v_cvt_pk_bf16_f32 v90, v104, v99
	v_cvt_pk_bf16_f32 v91, v106, v91
	global_store_dwordx4 v[96:97], v[88:91], off
	s_nop 1
	v_pk_mul_f32 v[88:89], v[84:85], v[172:173] op_sel:[1,1] op_sel_hi:[1,0]
	s_nop 0
	v_pk_fma_f32 v[90:91], v[84:85], v[172:173], v[88:89] neg_lo:[0,0,1] neg_hi:[0,0,1]
	v_pk_fma_f32 v[84:85], v[84:85], v[172:173], v[88:89] op_sel_hi:[0,1,1]
	v_mov_b32_e32 v84, v87
	v_pk_mul_f32 v[88:89], v[84:85], v[174:175] op_sel:[0,1] op_sel_hi:[0,0]
	v_pk_fma_f32 v[92:93], v[86:87], v[174:175], v[88:89] neg_lo:[0,0,1] neg_hi:[0,0,1]
	v_pk_fma_f32 v[86:87], v[86:87], v[174:175], v[88:89] op_sel_hi:[0,1,1]
	v_pk_mul_f32 v[88:89], v[80:81], v[168:169] op_sel:[1,1] op_sel_hi:[1,0]
	s_nop 0
	v_pk_fma_f32 v[94:95], v[80:81], v[168:169], v[88:89] neg_lo:[0,0,1] neg_hi:[0,0,1]
	v_pk_fma_f32 v[88:89], v[80:81], v[168:169], v[88:89] op_sel_hi:[0,1,1]
	v_mov_b32_e32 v80, v83
	v_pk_mul_f32 v[80:81], v[80:81], v[170:171] op_sel:[0,1] op_sel_hi:[0,0]
	v_pk_fma_f32 v[98:99], v[82:83], v[170:171], v[80:81] neg_lo:[0,0,1] neg_hi:[0,0,1]
	v_pk_fma_f32 v[82:83], v[82:83], v[170:171], v[80:81] op_sel_hi:[0,1,1]
	v_cvt_pk_bf16_f32 v80, v90, v85
	v_cvt_pk_bf16_f32 v81, v92, v87
	v_cvt_pk_bf16_f32 v82, v94, v89
	v_cvt_pk_bf16_f32 v83, v98, v83
	global_store_dwordx4 v[96:97], v[80:83], off offset:256
	s_nop 1
	s_waitcnt vmcnt(14)
	v_pk_mul_f32 v[82:83], v[76:77], v[164:165] op_sel:[1,1] op_sel_hi:[1,0]
	v_or_b32_e32 v80, 48, v214
	v_pk_fma_f32 v[84:85], v[76:77], v[164:165], v[82:83] neg_lo:[0,0,1] neg_hi:[0,0,1]
	v_pk_fma_f32 v[76:77], v[76:77], v[164:165], v[82:83] op_sel_hi:[0,1,1]
	v_mov_b32_e32 v76, v79
	v_pk_mul_f32 v[82:83], v[76:77], v[166:167] op_sel:[0,1] op_sel_hi:[0,0]
	v_pk_fma_f32 v[86:87], v[78:79], v[166:167], v[82:83] neg_lo:[0,0,1] neg_hi:[0,0,1]
	v_pk_fma_f32 v[78:79], v[78:79], v[166:167], v[82:83] op_sel_hi:[0,1,1]
	v_pk_mul_f32 v[82:83], v[72:73], v[160:161] op_sel:[1,1] op_sel_hi:[1,0]
	v_ashrrev_i32_e32 v81, 31, v80
	v_pk_fma_f32 v[88:89], v[72:73], v[160:161], v[82:83] neg_lo:[0,0,1] neg_hi:[0,0,1]
	v_pk_fma_f32 v[82:83], v[72:73], v[160:161], v[82:83] op_sel_hi:[0,1,1]
	v_mov_b32_e32 v72, v75
	v_pk_mul_f32 v[72:73], v[72:73], v[162:163] op_sel:[0,1] op_sel_hi:[0,0]
	v_lshlrev_b64 v[80:81], 10, v[80:81]
	v_pk_fma_f32 v[90:91], v[74:75], v[162:163], v[72:73] neg_lo:[0,0,1] neg_hi:[0,0,1]
	v_pk_fma_f32 v[74:75], v[74:75], v[162:163], v[72:73] op_sel_hi:[0,1,1]
	v_lshl_add_u64 v[80:81], v[218:219], 0, v[80:81]
	v_cvt_pk_bf16_f32 v72, v84, v77
	v_cvt_pk_bf16_f32 v73, v86, v79
	v_cvt_pk_bf16_f32 v74, v88, v83
	v_cvt_pk_bf16_f32 v75, v90, v75
	global_store_dwordx4 v[80:81], v[72:75], off
	s_nop 1
	v_pk_mul_f32 v[72:73], v[68:69], v[164:165] op_sel:[1,1] op_sel_hi:[1,0]
	s_nop 0
	v_pk_fma_f32 v[74:75], v[68:69], v[164:165], v[72:73] neg_lo:[0,0,1] neg_hi:[0,0,1]
	v_pk_fma_f32 v[68:69], v[68:69], v[164:165], v[72:73] op_sel_hi:[0,1,1]
	v_mov_b32_e32 v68, v71
	v_pk_mul_f32 v[72:73], v[68:69], v[166:167] op_sel:[0,1] op_sel_hi:[0,0]
	v_pk_fma_f32 v[76:77], v[70:71], v[166:167], v[72:73] neg_lo:[0,0,1] neg_hi:[0,0,1]
	v_pk_fma_f32 v[70:71], v[70:71], v[166:167], v[72:73] op_sel_hi:[0,1,1]
	v_pk_mul_f32 v[72:73], v[64:65], v[160:161] op_sel:[1,1] op_sel_hi:[1,0]
	s_nop 0
	v_pk_fma_f32 v[78:79], v[64:65], v[160:161], v[72:73] neg_lo:[0,0,1] neg_hi:[0,0,1]
	v_pk_fma_f32 v[72:73], v[64:65], v[160:161], v[72:73] op_sel_hi:[0,1,1]
	v_mov_b32_e32 v64, v67
	v_pk_mul_f32 v[64:65], v[64:65], v[162:163] op_sel:[0,1] op_sel_hi:[0,0]
	v_pk_fma_f32 v[82:83], v[66:67], v[162:163], v[64:65] neg_lo:[0,0,1] neg_hi:[0,0,1]
	v_pk_fma_f32 v[66:67], v[66:67], v[162:163], v[64:65] op_sel_hi:[0,1,1]
	v_cvt_pk_bf16_f32 v64, v74, v69
	v_cvt_pk_bf16_f32 v65, v76, v71
	v_cvt_pk_bf16_f32 v66, v78, v73
	v_cvt_pk_bf16_f32 v67, v82, v67
	global_store_dwordx4 v[80:81], v[64:67], off offset:256
	s_nop 1
	s_waitcnt vmcnt(14)
	v_pk_mul_f32 v[66:67], v[60:61], v[156:157] op_sel:[1,1] op_sel_hi:[1,0]
	v_lshl_add_u64 v[64:65], v[216:217], 0, s[16:17]
	v_pk_fma_f32 v[68:69], v[60:61], v[156:157], v[66:67] neg_lo:[0,0,1] neg_hi:[0,0,1]
	v_pk_fma_f32 v[60:61], v[60:61], v[156:157], v[66:67] op_sel_hi:[0,1,1]
	v_mov_b32_e32 v60, v63
	v_pk_mul_f32 v[66:67], v[60:61], v[158:159] op_sel:[0,1] op_sel_hi:[0,0]
	v_pk_fma_f32 v[70:71], v[62:63], v[158:159], v[66:67] neg_lo:[0,0,1] neg_hi:[0,0,1]
	v_pk_fma_f32 v[62:63], v[62:63], v[158:159], v[66:67] op_sel_hi:[0,1,1]
	v_pk_mul_f32 v[66:67], v[56:57], v[152:153] op_sel:[1,1] op_sel_hi:[1,0]
	v_add_co_u32_e32 v60, vcc, s71, v216
	v_pk_fma_f32 v[72:73], v[56:57], v[152:153], v[66:67] neg_lo:[0,0,1] neg_hi:[0,0,1]
	v_pk_fma_f32 v[66:67], v[56:57], v[152:153], v[66:67] op_sel_hi:[0,1,1]
	v_mov_b32_e32 v56, v59
	v_pk_mul_f32 v[56:57], v[56:57], v[154:155] op_sel:[0,1] op_sel_hi:[0,0]
	v_pk_fma_f32 v[74:75], v[58:59], v[154:155], v[56:57] neg_lo:[0,0,1] neg_hi:[0,0,1]
	v_pk_fma_f32 v[58:59], v[58:59], v[154:155], v[56:57] op_sel_hi:[0,1,1]
	v_cvt_pk_bf16_f32 v56, v68, v61
	v_cvt_pk_bf16_f32 v57, v70, v63
	v_cvt_pk_bf16_f32 v58, v72, v67
	v_cvt_pk_bf16_f32 v59, v74, v59
	v_addc_co_u32_e32 v61, vcc, 0, v217, vcc
	global_store_dwordx4 v[60:61], v[56:59], off
	s_nop 1
	v_pk_mul_f32 v[56:57], v[52:53], v[156:157] op_sel:[1,1] op_sel_hi:[1,0]
	s_nop 0
	v_pk_fma_f32 v[58:59], v[52:53], v[156:157], v[56:57] neg_lo:[0,0,1] neg_hi:[0,0,1]
	v_pk_fma_f32 v[52:53], v[52:53], v[156:157], v[56:57] op_sel_hi:[0,1,1]
	v_mov_b32_e32 v52, v55
	v_pk_mul_f32 v[56:57], v[52:53], v[158:159] op_sel:[0,1] op_sel_hi:[0,0]
	v_pk_fma_f32 v[60:61], v[54:55], v[158:159], v[56:57] neg_lo:[0,0,1] neg_hi:[0,0,1]
	v_pk_fma_f32 v[54:55], v[54:55], v[158:159], v[56:57] op_sel_hi:[0,1,1]
	v_pk_mul_f32 v[56:57], v[44:45], v[152:153] op_sel:[1,1] op_sel_hi:[1,0]
	s_nop 0
	v_pk_fma_f32 v[62:63], v[44:45], v[152:153], v[56:57] neg_lo:[0,0,1] neg_hi:[0,0,1]
	v_pk_fma_f32 v[56:57], v[44:45], v[152:153], v[56:57] op_sel_hi:[0,1,1]
	v_mov_b32_e32 v44, v47
	v_pk_mul_f32 v[44:45], v[44:45], v[154:155] op_sel:[0,1] op_sel_hi:[0,0]
	v_pk_fma_f32 v[66:67], v[46:47], v[154:155], v[44:45] neg_lo:[0,0,1] neg_hi:[0,0,1]
	v_pk_fma_f32 v[46:47], v[46:47], v[154:155], v[44:45] op_sel_hi:[0,1,1]
	v_cvt_pk_bf16_f32 v44, v58, v53
	v_cvt_pk_bf16_f32 v45, v60, v55
	v_cvt_pk_bf16_f32 v46, v62, v57
	v_cvt_pk_bf16_f32 v47, v66, v47
	global_store_dwordx4 v[64:65], v[44:47], off offset:256
	s_nop 1
	s_waitcnt vmcnt(14)
	v_pk_mul_f32 v[46:47], v[48:49], v[148:149] op_sel:[1,1] op_sel_hi:[1,0]
	v_lshl_add_u64 v[44:45], v[216:217], 0, s[18:19]
	v_pk_fma_f32 v[52:53], v[48:49], v[148:149], v[46:47] neg_lo:[0,0,1] neg_hi:[0,0,1]
	v_pk_fma_f32 v[46:47], v[48:49], v[148:149], v[46:47] op_sel_hi:[0,1,1]
	v_mov_b32_e32 v46, v51
	v_pk_mul_f32 v[48:49], v[46:47], v[150:151] op_sel:[0,1] op_sel_hi:[0,0]
	v_pk_fma_f32 v[54:55], v[50:51], v[150:151], v[48:49] neg_lo:[0,0,1] neg_hi:[0,0,1]
	v_pk_fma_f32 v[48:49], v[50:51], v[150:151], v[48:49] op_sel_hi:[0,1,1]
	v_pk_mul_f32 v[50:51], v[40:41], v[144:145] op_sel:[1,1] op_sel_hi:[1,0]
	v_add_co_u32_e32 v46, vcc, s74, v216
	v_pk_fma_f32 v[56:57], v[40:41], v[144:145], v[50:51] neg_lo:[0,0,1] neg_hi:[0,0,1]
	v_pk_fma_f32 v[50:51], v[40:41], v[144:145], v[50:51] op_sel_hi:[0,1,1]
	v_mov_b32_e32 v40, v43
	v_pk_mul_f32 v[40:41], v[40:41], v[146:147] op_sel:[0,1] op_sel_hi:[0,0]
	v_pk_fma_f32 v[58:59], v[42:43], v[146:147], v[40:41] neg_lo:[0,0,1] neg_hi:[0,0,1]
	v_pk_fma_f32 v[42:43], v[42:43], v[146:147], v[40:41] op_sel_hi:[0,1,1]
	v_cvt_pk_bf16_f32 v40, v52, v47
	v_cvt_pk_bf16_f32 v41, v54, v49
	v_cvt_pk_bf16_f32 v42, v56, v51
	v_cvt_pk_bf16_f32 v43, v58, v43
	v_addc_co_u32_e32 v47, vcc, 0, v217, vcc
	global_store_dwordx4 v[46:47], v[40:43], off
	s_nop 1
	v_pk_mul_f32 v[40:41], v[36:37], v[148:149] op_sel:[1,1] op_sel_hi:[1,0]
	s_nop 0
	v_pk_fma_f32 v[42:43], v[36:37], v[148:149], v[40:41] neg_lo:[0,0,1] neg_hi:[0,0,1]
	v_pk_fma_f32 v[36:37], v[36:37], v[148:149], v[40:41] op_sel_hi:[0,1,1]
	v_mov_b32_e32 v36, v39
	v_pk_mul_f32 v[40:41], v[36:37], v[150:151] op_sel:[0,1] op_sel_hi:[0,0]
	v_pk_fma_f32 v[46:47], v[38:39], v[150:151], v[40:41] neg_lo:[0,0,1] neg_hi:[0,0,1]
	v_pk_fma_f32 v[38:39], v[38:39], v[150:151], v[40:41] op_sel_hi:[0,1,1]
	v_pk_mul_f32 v[40:41], v[28:29], v[144:145] op_sel:[1,1] op_sel_hi:[1,0]
	s_nop 0
	v_pk_fma_f32 v[48:49], v[28:29], v[144:145], v[40:41] neg_lo:[0,0,1] neg_hi:[0,0,1]
	v_pk_fma_f32 v[40:41], v[28:29], v[144:145], v[40:41] op_sel_hi:[0,1,1]
	v_mov_b32_e32 v28, v31
	v_pk_mul_f32 v[28:29], v[28:29], v[146:147] op_sel:[0,1] op_sel_hi:[0,0]
	v_pk_fma_f32 v[50:51], v[30:31], v[146:147], v[28:29] neg_lo:[0,0,1] neg_hi:[0,0,1]
	v_pk_fma_f32 v[30:31], v[30:31], v[146:147], v[28:29] op_sel_hi:[0,1,1]
	v_cvt_pk_bf16_f32 v28, v42, v37
	v_cvt_pk_bf16_f32 v29, v46, v39
	v_cvt_pk_bf16_f32 v30, v48, v41
	v_cvt_pk_bf16_f32 v31, v50, v31
	global_store_dwordx4 v[44:45], v[28:31], off offset:256
	s_nop 1
	s_waitcnt vmcnt(14)
	v_pk_mul_f32 v[30:31], v[32:33], v[140:141] op_sel:[1,1] op_sel_hi:[1,0]
	v_lshl_add_u64 v[28:29], v[216:217], 0, s[20:21]
	v_pk_fma_f32 v[36:37], v[32:33], v[140:141], v[30:31] neg_lo:[0,0,1] neg_hi:[0,0,1]
	v_pk_fma_f32 v[30:31], v[32:33], v[140:141], v[30:31] op_sel_hi:[0,1,1]
	v_mov_b32_e32 v30, v35
	v_pk_mul_f32 v[32:33], v[30:31], v[142:143] op_sel:[0,1] op_sel_hi:[0,0]
	v_pk_fma_f32 v[38:39], v[34:35], v[142:143], v[32:33] neg_lo:[0,0,1] neg_hi:[0,0,1]
	v_pk_fma_f32 v[32:33], v[34:35], v[142:143], v[32:33] op_sel_hi:[0,1,1]
	v_pk_mul_f32 v[34:35], v[24:25], v[136:137] op_sel:[1,1] op_sel_hi:[1,0]
	v_add_co_u32_e32 v30, vcc, s75, v216
	v_pk_fma_f32 v[40:41], v[24:25], v[136:137], v[34:35] neg_lo:[0,0,1] neg_hi:[0,0,1]
	v_pk_fma_f32 v[34:35], v[24:25], v[136:137], v[34:35] op_sel_hi:[0,1,1]
	v_mov_b32_e32 v24, v27
	v_pk_mul_f32 v[24:25], v[24:25], v[138:139] op_sel:[0,1] op_sel_hi:[0,0]
	v_pk_fma_f32 v[42:43], v[26:27], v[138:139], v[24:25] neg_lo:[0,0,1] neg_hi:[0,0,1]
	v_pk_fma_f32 v[26:27], v[26:27], v[138:139], v[24:25] op_sel_hi:[0,1,1]
	v_cvt_pk_bf16_f32 v24, v36, v31
	v_cvt_pk_bf16_f32 v25, v38, v33
	v_cvt_pk_bf16_f32 v26, v40, v35
	v_cvt_pk_bf16_f32 v27, v42, v27
	v_addc_co_u32_e32 v31, vcc, 0, v217, vcc
	global_store_dwordx4 v[30:31], v[24:27], off
	s_nop 1
	v_pk_mul_f32 v[24:25], v[20:21], v[140:141] op_sel:[1,1] op_sel_hi:[1,0]
	s_nop 0
	v_pk_fma_f32 v[26:27], v[20:21], v[140:141], v[24:25] neg_lo:[0,0,1] neg_hi:[0,0,1]
	v_pk_fma_f32 v[20:21], v[20:21], v[140:141], v[24:25] op_sel_hi:[0,1,1]
	v_mov_b32_e32 v20, v23
	v_pk_mul_f32 v[24:25], v[20:21], v[142:143] op_sel:[0,1] op_sel_hi:[0,0]
	v_pk_fma_f32 v[30:31], v[22:23], v[142:143], v[24:25] neg_lo:[0,0,1] neg_hi:[0,0,1]
	v_pk_fma_f32 v[22:23], v[22:23], v[142:143], v[24:25] op_sel_hi:[0,1,1]
	v_pk_mul_f32 v[24:25], v[12:13], v[136:137] op_sel:[1,1] op_sel_hi:[1,0]
	s_nop 0
	v_pk_fma_f32 v[32:33], v[12:13], v[136:137], v[24:25] neg_lo:[0,0,1] neg_hi:[0,0,1]
	v_pk_fma_f32 v[24:25], v[12:13], v[136:137], v[24:25] op_sel_hi:[0,1,1]
	v_mov_b32_e32 v12, v15
	v_pk_mul_f32 v[12:13], v[12:13], v[138:139] op_sel:[0,1] op_sel_hi:[0,0]
	v_pk_fma_f32 v[34:35], v[14:15], v[138:139], v[12:13] neg_lo:[0,0,1] neg_hi:[0,0,1]
	v_pk_fma_f32 v[14:15], v[14:15], v[138:139], v[12:13] op_sel_hi:[0,1,1]
	v_cvt_pk_bf16_f32 v12, v26, v21
	v_cvt_pk_bf16_f32 v13, v30, v23
	v_cvt_pk_bf16_f32 v14, v32, v25
	v_cvt_pk_bf16_f32 v15, v34, v15
	global_store_dwordx4 v[28:29], v[12:15], off offset:256
	s_nop 1
	s_waitcnt vmcnt(14)
	v_pk_mul_f32 v[14:15], v[16:17], v[132:133] op_sel:[1,1] op_sel_hi:[1,0]
	v_lshl_add_u64 v[12:13], v[216:217], 0, s[22:23]
	v_pk_fma_f32 v[20:21], v[16:17], v[132:133], v[14:15] neg_lo:[0,0,1] neg_hi:[0,0,1]
	v_pk_fma_f32 v[14:15], v[16:17], v[132:133], v[14:15] op_sel_hi:[0,1,1]
	v_mov_b32_e32 v14, v19
	v_pk_mul_f32 v[16:17], v[14:15], v[134:135] op_sel:[0,1] op_sel_hi:[0,0]
	v_pk_fma_f32 v[22:23], v[18:19], v[134:135], v[16:17] neg_lo:[0,0,1] neg_hi:[0,0,1]
	v_pk_fma_f32 v[16:17], v[18:19], v[134:135], v[16:17] op_sel_hi:[0,1,1]
	v_pk_mul_f32 v[18:19], v[8:9], v[128:129] op_sel:[1,1] op_sel_hi:[1,0]
	v_add_co_u32_e32 v14, vcc, s78, v216
	v_pk_fma_f32 v[24:25], v[8:9], v[128:129], v[18:19] neg_lo:[0,0,1] neg_hi:[0,0,1]
	v_pk_fma_f32 v[18:19], v[8:9], v[128:129], v[18:19] op_sel_hi:[0,1,1]
	v_mov_b32_e32 v8, v11
	v_pk_mul_f32 v[8:9], v[8:9], v[130:131] op_sel:[0,1] op_sel_hi:[0,0]
	v_pk_fma_f32 v[26:27], v[10:11], v[130:131], v[8:9] neg_lo:[0,0,1] neg_hi:[0,0,1]
	v_pk_fma_f32 v[10:11], v[10:11], v[130:131], v[8:9] op_sel_hi:[0,1,1]
	v_cvt_pk_bf16_f32 v8, v20, v15
	v_cvt_pk_bf16_f32 v9, v22, v17
	v_cvt_pk_bf16_f32 v10, v24, v19
	v_cvt_pk_bf16_f32 v11, v26, v11
	v_addc_co_u32_e32 v15, vcc, 0, v217, vcc
	global_store_dwordx4 v[14:15], v[8:11], off
	s_nop 1
	v_pk_mul_f32 v[8:9], v[4:5], v[132:133] op_sel:[1,1] op_sel_hi:[1,0]
	s_nop 0
	v_pk_fma_f32 v[10:11], v[4:5], v[132:133], v[8:9] neg_lo:[0,0,1] neg_hi:[0,0,1]
	v_pk_fma_f32 v[4:5], v[4:5], v[132:133], v[8:9] op_sel_hi:[0,1,1]
	v_mov_b32_e32 v4, v7
	v_pk_mul_f32 v[8:9], v[4:5], v[134:135] op_sel:[0,1] op_sel_hi:[0,0]
	v_pk_fma_f32 v[14:15], v[6:7], v[134:135], v[8:9] neg_lo:[0,0,1] neg_hi:[0,0,1]
	v_pk_fma_f32 v[6:7], v[6:7], v[134:135], v[8:9] op_sel_hi:[0,1,1]
	v_pk_mul_f32 v[8:9], v[0:1], v[128:129] op_sel:[1,1] op_sel_hi:[1,0]
	s_nop 0
	v_pk_fma_f32 v[16:17], v[0:1], v[128:129], v[8:9] neg_lo:[0,0,1] neg_hi:[0,0,1]
	v_pk_fma_f32 v[8:9], v[0:1], v[128:129], v[8:9] op_sel_hi:[0,1,1]
	v_mov_b32_e32 v0, v3
	v_pk_mul_f32 v[0:1], v[0:1], v[130:131] op_sel:[0,1] op_sel_hi:[0,0]
	v_pk_fma_f32 v[18:19], v[2:3], v[130:131], v[0:1] neg_lo:[0,0,1] neg_hi:[0,0,1]
	v_pk_fma_f32 v[2:3], v[2:3], v[130:131], v[0:1] op_sel_hi:[0,1,1]
	v_cvt_pk_bf16_f32 v0, v10, v5
	v_cvt_pk_bf16_f32 v1, v14, v7
	v_cvt_pk_bf16_f32 v2, v16, v9
	v_cvt_pk_bf16_f32 v3, v18, v3
	global_store_dwordx4 v[12:13], v[0:3], off offset:256
	s_andn2_b64 vcc, exec, s[4:5]
	s_mov_b64 s[4:5], -1
	s_cbranch_vccnz .LBB0_337
